# static priority raise (s_setprio 1) for waves 4-7 inside the attention unit loop
# speedup vs baseline: 1.0036x; 1.0036x over previous
.LBB0_748:
	s_or_b64 exec, exec, s[4:5]
	s_add_u32 s52, s6, 0x14000000
	s_addc_u32 s53, s7, 0
	s_add_u32 s55, s6, 0x1a000000
	s_addc_u32 s4, s7, 0
	v_add_u32_e32 v2, s8, v138
	s_add_u32 s0, s50, s0
	v_ashrrev_i32_e32 v3, 31, v2
	s_addc_u32 s1, s51, s1
	v_lshlrev_b64 v[2:3], 7, v[2:3]
	v_writelane_b32 v254, s4, 44
	v_lshl_add_u64 v[2:3], s[0:1], 0, v[2:3]
	v_mov_b32_e32 v131, v1
	s_movk_i32 s4, 0x90
	v_lshl_add_u64 v[2:3], v[2:3], 0, v[130:131]
	v_mul_lo_u32 v0, v136, s4
	v_and_b32_e32 v50, 15, v42
	v_bfe_u32 v51, v42, 4, 2
	global_load_dwordx4 v[40:43], v[2:3], off offset:64
	global_load_dwordx4 v[44:47], v[2:3], off
	v_add3_u32 v139, 0, v0, v128
	v_lshlrev_b32_e32 v0, 2, v49
	v_lshlrev_b32_e32 v2, 1, v48
	v_add3_u32 v2, 0, v0, v2
	s_add_u32 s0, s6, 0x21000000
	v_lshlrev_b32_e32 v0, 2, v51
	v_and_b32_e32 v49, 0xffffffe0, v49
	v_writelane_b32 v254, s0, 45
	s_addc_u32 s0, s7, 0
	v_add_u32_e32 v52, 0x80, v138
	v_or_b32_e32 v62, v49, v0
	v_writelane_b32 v254, s0, 46
	v_cmp_ge_i32_e32 vcc, v62, v138
	v_cmp_le_i32_e64 s[0:1], v62, v52
	s_and_b64 s[0:1], vcc, s[0:1]
	v_or_b32_e32 v63, 1, v62
	v_writelane_b32 v254, s0, 6
	v_cmp_ge_i32_e32 vcc, v63, v138
	v_or_b32_e32 v63, 2, v62
	v_writelane_b32 v254, s1, 7
	v_cmp_lt_i32_e64 s[0:1], v62, v52
	s_and_b64 s[0:1], vcc, s[0:1]
	v_cmp_ge_i32_e32 vcc, v63, v138
	v_writelane_b32 v254, s0, 12
	v_or_b32_e32 v64, 3, v62
	v_or_b32_e32 v53, 16, v49
	v_writelane_b32 v254, s1, 13
	v_cmp_le_i32_e64 s[0:1], v63, v52
	s_and_b64 s[0:1], vcc, s[0:1]
	v_cmp_ge_i32_e32 vcc, v64, v138
	v_writelane_b32 v254, s0, 14
	v_or_b32_e32 v65, v53, v0
	v_or_b32_e32 v66, 1, v65
	v_writelane_b32 v254, s1, 15
	v_cmp_le_i32_e64 s[0:1], v64, v52
	s_and_b64 s[0:1], vcc, s[0:1]
	v_cmp_ge_i32_e32 vcc, v65, v138
	v_writelane_b32 v254, s0, 16
	v_or_b32_e32 v67, 3, v65
	v_add_u32_e32 v54, 32, v49
	v_writelane_b32 v254, s1, 17
	v_cmp_le_i32_e64 s[0:1], v65, v52
	s_and_b64 s[0:1], vcc, s[0:1]
	v_cmp_ge_i32_e32 vcc, v66, v138
	v_writelane_b32 v254, s0, 18
	v_or_b32_e32 v66, 2, v65
	v_or_b32_e32 v68, v54, v0
	v_writelane_b32 v254, s1, 19
	v_cmp_lt_i32_e64 s[0:1], v65, v52
	s_and_b64 s[0:1], vcc, s[0:1]
	v_cmp_ge_i32_e32 vcc, v66, v138
	v_writelane_b32 v254, s0, 20
	v_or_b32_e32 v69, 1, v68
	v_or_b32_e32 v70, 3, v68
	v_writelane_b32 v254, s1, 21
	v_cmp_le_i32_e64 s[0:1], v66, v52
	s_and_b64 s[0:1], vcc, s[0:1]
	v_cmp_ge_i32_e32 vcc, v67, v138
	v_writelane_b32 v254, s0, 22
	v_add_u32_e32 v55, 48, v49
	v_or_b32_e32 v71, v55, v0
	v_writelane_b32 v254, s1, 23
	v_cmp_le_i32_e64 s[0:1], v67, v52
	s_and_b64 s[0:1], vcc, s[0:1]
	v_cmp_ge_i32_e32 vcc, v68, v138
	v_writelane_b32 v254, s0, 24
	v_or_b32_e32 v72, 1, v71
	v_or_b32_e32 v73, 3, v71
	v_writelane_b32 v254, s1, 25
	v_cmp_le_i32_e64 s[0:1], v68, v52
	s_and_b64 s[0:1], vcc, s[0:1]
	v_cmp_ge_i32_e32 vcc, v69, v138
	v_writelane_b32 v254, s0, 26
	v_or_b32_e32 v69, 2, v68
	v_add_u32_e32 v56, 64, v49
	v_writelane_b32 v254, s1, 27
	v_cmp_lt_i32_e64 s[0:1], v68, v52
	s_and_b64 s[0:1], vcc, s[0:1]
	v_cmp_ge_i32_e32 vcc, v69, v138
	v_writelane_b32 v254, s0, 28
	v_or_b32_e32 v74, v56, v0
	v_or_b32_e32 v75, 1, v74
	v_writelane_b32 v254, s1, 29
	v_cmp_le_i32_e64 s[0:1], v69, v52
	s_and_b64 s[0:1], vcc, s[0:1]
	v_cmp_ge_i32_e32 vcc, v70, v138
	v_writelane_b32 v254, s0, 30
	v_or_b32_e32 v76, 3, v74
	v_add_u32_e32 v57, 0x50, v49
	v_writelane_b32 v254, s1, 31
	v_cmp_le_i32_e64 s[0:1], v70, v52
	s_and_b64 s[0:1], vcc, s[0:1]
	v_cmp_ge_i32_e32 vcc, v71, v138
	v_writelane_b32 v254, s0, 32
	v_or_b32_e32 v77, v57, v0
	v_or_b32_e32 v78, 1, v77
	v_writelane_b32 v254, s1, 33
	v_cmp_le_i32_e64 s[0:1], v71, v52
	s_and_b64 s[0:1], vcc, s[0:1]
	v_cmp_ge_i32_e32 vcc, v72, v138
	v_writelane_b32 v254, s0, 34
	v_or_b32_e32 v72, 2, v71
	v_or_b32_e32 v79, 3, v77
	v_writelane_b32 v254, s1, 35
	v_cmp_lt_i32_e64 s[0:1], v71, v52
	s_and_b64 s[0:1], vcc, s[0:1]
	v_cmp_ge_i32_e32 vcc, v72, v138
	v_writelane_b32 v254, s0, 36
	v_add_u32_e32 v58, 0x60, v49
	v_or_b32_e32 v80, v58, v0
	v_writelane_b32 v254, s1, 37
	v_cmp_le_i32_e64 s[0:1], v72, v52
	s_and_b64 s[0:1], vcc, s[0:1]
	v_cmp_ge_i32_e32 vcc, v73, v138
	v_writelane_b32 v254, s0, 38
	v_or_b32_e32 v81, 1, v80
	v_or_b32_e32 v82, 3, v80
	v_writelane_b32 v254, s1, 39
	v_cmp_le_i32_e64 s[0:1], v73, v52
	s_and_b64 s[0:1], vcc, s[0:1]
	v_cmp_ge_i32_e32 vcc, v74, v138
	v_writelane_b32 v254, s0, 40
	v_add_u32_e32 v59, 0x70, v49
	v_or_b32_e32 v83, v59, v0
	v_writelane_b32 v254, s1, 41
	v_cmp_le_i32_e64 s[0:1], v74, v52
	s_and_b64 s[0:1], vcc, s[0:1]
	v_cmp_ge_i32_e32 vcc, v75, v138
	v_writelane_b32 v254, s0, 42
	v_or_b32_e32 v75, 2, v74
	v_or_b32_e32 v84, 1, v83
	v_writelane_b32 v254, s1, 43
	v_cmp_lt_i32_e64 s[0:1], v74, v52
	s_and_b64 s[0:1], vcc, s[0:1]
	v_cmp_ge_i32_e32 vcc, v75, v138
	v_writelane_b32 v253, s0, 54
	v_or_b32_e32 v85, 3, v83
	v_add_u32_e32 v60, 0x80, v49
	v_writelane_b32 v253, s1, 55
	v_cmp_le_i32_e64 s[0:1], v75, v52
	s_and_b64 s[0:1], vcc, s[0:1]
	v_cmp_ge_i32_e32 vcc, v76, v138
	v_writelane_b32 v253, s0, 52
	v_or_b32_e32 v86, v60, v0
	v_or_b32_e32 v87, 1, v86
	v_writelane_b32 v253, s1, 53
	v_cmp_le_i32_e64 s[0:1], v76, v52
	s_and_b64 s[0:1], vcc, s[0:1]
	v_cmp_ge_i32_e32 vcc, v77, v138
	v_writelane_b32 v253, s0, 49
	v_or_b32_e32 v129, 3, v86
	v_add_u32_e32 v61, 0x90, v49
	v_writelane_b32 v253, s1, 50
	v_cmp_le_i32_e64 s[0:1], v77, v52
	s_and_b64 s[0:1], vcc, s[0:1]
	v_cmp_ge_i32_e32 vcc, v78, v138
	v_writelane_b32 v254, s0, 0
	v_or_b32_e32 v78, 2, v77
	v_or_b32_e32 v131, v61, v0
	v_writelane_b32 v254, s1, 1
	v_cmp_lt_i32_e64 s[0:1], v77, v52
	s_and_b64 s[0:1], vcc, s[0:1]
	v_cmp_ge_i32_e32 vcc, v78, v138
	v_writelane_b32 v253, s0, 56
	v_or_b32_e32 v134, 1, v131
	v_or_b32_e32 v135, 2, v131
	v_writelane_b32 v253, s1, 57
	v_cmp_le_i32_e64 s[0:1], v78, v52
	s_and_b64 s[0:1], vcc, s[0:1]
	v_cmp_ge_i32_e32 vcc, v79, v138
	v_writelane_b32 v253, s0, 58
	v_or_b32_e32 v152, 3, v131
	s_movk_i32 s40, 0x7e
	v_writelane_b32 v253, s1, 59
	v_cmp_le_i32_e64 s[0:1], v79, v52
	s_and_b64 s[0:1], vcc, s[0:1]
	v_cmp_ge_i32_e32 vcc, v80, v138
	v_writelane_b32 v253, s0, 60
	v_lshlrev_b32_e32 v3, 3, v51
	s_movk_i32 s44, 0x7f
	v_writelane_b32 v253, s1, 61
	v_cmp_le_i32_e64 s[0:1], v80, v52
	s_and_b64 s[0:1], vcc, s[0:1]
	v_cmp_ge_i32_e32 vcc, v81, v138
	v_writelane_b32 v253, s0, 62
	v_or_b32_e32 v81, 2, v80
	v_cmp_lt_i32_e64 s[82:83], s93, v77
	v_writelane_b32 v253, s1, 63
	v_cmp_lt_i32_e64 s[0:1], v80, v52
	s_and_b64 s[0:1], vcc, s[0:1]
	v_cmp_ge_i32_e32 vcc, v81, v138
	v_writelane_b32 v254, s0, 2
	v_cmp_lt_i32_e64 s[84:85], s40, v77
	v_cmp_lt_i32_e64 s[86:87], s93, v78
	v_writelane_b32 v254, s1, 3
	v_cmp_le_i32_e64 s[0:1], v81, v52
	s_and_b64 s[0:1], vcc, s[0:1]
	v_cmp_ge_i32_e32 vcc, v82, v138
	v_writelane_b32 v254, s0, 47
	v_cmp_lt_i32_e64 s[88:89], s93, v79
	v_cmp_lt_i32_e64 s[90:91], s93, v80
	v_writelane_b32 v254, s1, 48
	v_cmp_le_i32_e64 s[0:1], v82, v52
	s_and_b64 s[0:1], vcc, s[0:1]
	v_cmp_ge_i32_e32 vcc, v83, v138
	v_writelane_b32 v254, s0, 49
	v_cmp_lt_i32_e64 s[66:67], s44, v81
	v_cmp_lt_i32_e64 s[96:97], s44, v82
	v_writelane_b32 v254, s1, 50
	v_cmp_le_i32_e64 s[0:1], v83, v52
	s_and_b64 s[0:1], vcc, s[0:1]
	v_cmp_ge_i32_e32 vcc, v84, v138
	v_writelane_b32 v254, s0, 51
	v_or_b32_e32 v84, 2, v83
	v_cmp_lt_i32_e64 s[36:37], s44, v83
	v_writelane_b32 v254, s1, 52
	v_cmp_lt_i32_e64 s[0:1], v83, v52
	s_and_b64 s[0:1], vcc, s[0:1]
	v_cmp_ge_i32_e32 vcc, v84, v138
	v_writelane_b32 v254, s0, 53
	v_cmp_lt_i32_e64 s[6:7], s44, v85
	v_cmp_lt_i32_e64 s[8:9], s44, v86
	v_writelane_b32 v254, s1, 54
	v_cmp_le_i32_e64 s[0:1], v84, v52
	s_and_b64 s[0:1], vcc, s[0:1]
	v_cmp_ge_i32_e32 vcc, v85, v138
	v_writelane_b32 v254, s0, 55
	v_cmp_lt_i32_e64 s[10:11], s40, v86
	v_cmp_lt_i32_e64 s[34:35], s44, v129
	v_writelane_b32 v254, s1, 56
	v_cmp_le_i32_e64 s[0:1], v85, v52
	s_and_b64 s[0:1], vcc, s[0:1]
	v_cmp_ge_i32_e32 vcc, v86, v138
	v_writelane_b32 v254, s0, 57
	v_cmp_lt_i32_e64 s[38:39], s44, v131
	v_cmp_lt_i32_e64 s[42:43], s44, v135
	v_writelane_b32 v254, s1, 58
	v_cmp_le_i32_e64 s[0:1], v86, v52
	s_and_b64 s[0:1], vcc, s[0:1]
	v_cmp_ge_i32_e32 vcc, v87, v138
	v_writelane_b32 v254, s0, 59
	v_or_b32_e32 v87, 2, v86
	v_cmp_lt_i32_e64 s[30:31], s44, v87
	v_writelane_b32 v254, s1, 60
	v_cmp_lt_i32_e64 s[0:1], v86, v52
	s_and_b64 s[0:1], vcc, s[0:1]
	v_cmp_ge_i32_e32 vcc, v87, v138
	v_writelane_b32 v254, s0, 61
	s_nop 1
	v_writelane_b32 v254, s1, 62
	v_cmp_le_i32_e64 s[0:1], v87, v52
	s_and_b64 s[0:1], vcc, s[0:1]
	v_cmp_ge_i32_e32 vcc, v129, v138
	v_writelane_b32 v254, s0, 63
	s_nop 1
	v_writelane_b32 v255, s1, 0
	v_cmp_le_i32_e64 s[0:1], v129, v52
	s_and_b64 s[0:1], vcc, s[0:1]
	v_cmp_ge_i32_e32 vcc, v131, v138
	v_writelane_b32 v255, s0, 1
	s_nop 1
	v_writelane_b32 v255, s1, 2
	v_cmp_le_i32_e64 s[0:1], v131, v52
	s_and_b64 s[0:1], vcc, s[0:1]
	v_cmp_ge_i32_e32 vcc, v134, v138
	v_writelane_b32 v255, s0, 3
	v_lshlrev_b32_e32 v134, 1, v0
	s_nop 0
	v_writelane_b32 v255, s1, 4
	v_cmp_lt_i32_e64 s[0:1], v131, v52
	s_and_b64 s[0:1], vcc, s[0:1]
	v_cmp_ge_i32_e32 vcc, v135, v138
	v_writelane_b32 v255, s0, 5
	s_nop 1
	v_writelane_b32 v255, s1, 6
	v_cmp_le_i32_e64 s[0:1], v135, v52
	s_and_b64 s[0:1], vcc, s[0:1]
	v_cmp_ge_i32_e32 vcc, v152, v138
	v_writelane_b32 v255, s0, 7
	s_nop 1
	v_writelane_b32 v255, s1, 8
	v_cmp_le_i32_e64 s[0:1], v152, v52
	s_and_b64 s[0:1], vcc, s[0:1]
	v_mul_u32_u24_e32 v52, 0x220, v48
	v_writelane_b32 v255, s0, 9
	v_add_u32_e32 v164, v2, v52
	s_nop 0
	v_writelane_b32 v255, s1, 10
	v_cmp_eq_u32_e64 s[0:1], 0, v51
	s_nop 1
	v_writelane_b32 v255, s0, 11
	s_nop 1
	v_writelane_b32 v255, s1, 12
	s_movk_i32 s0, 0x220
	v_mad_u32_u24 v140, v48, s0, v2
	v_cmp_lt_i32_e64 s[0:1], s93, v62
	v_or_b32_e32 v48, v49, v50
	v_mul_lo_u32 v48, v48, s4
	v_writelane_b32 v255, s0, 13
	v_lshlrev_b32_e32 v49, 4, v51
	v_add3_u32 v141, 0, v48, v49
	v_writelane_b32 v255, s1, 14
	v_cmp_lt_i32_e64 s[0:1], s40, v62
	v_or_b32_e32 v48, v53, v50
	v_mul_lo_u32 v48, v48, s4
	v_writelane_b32 v255, s0, 15
	v_add3_u32 v142, 0, v48, v49
	v_or_b32_e32 v48, v54, v50
	v_writelane_b32 v255, s1, 16
	v_cmp_lt_i32_e64 s[0:1], s93, v63
	v_mul_lo_u32 v48, v48, s4
	v_add3_u32 v143, 0, v48, v49
	v_writelane_b32 v255, s0, 17
	v_or_b32_e32 v48, v55, v50
	v_mul_lo_u32 v48, v48, s4
	v_writelane_b32 v255, s1, 18
	v_cmp_lt_i32_e64 s[0:1], s93, v64
	v_add3_u32 v144, 0, v48, v49
	v_or_b32_e32 v48, v56, v50
	v_writelane_b32 v255, s0, 19
	v_mul_lo_u32 v48, v48, s4
	v_add3_u32 v145, 0, v48, v49
	v_writelane_b32 v255, s1, 20
	v_cmp_lt_i32_e64 s[0:1], s93, v65
	v_or_b32_e32 v48, v57, v50
	v_mul_lo_u32 v48, v48, s4
	v_writelane_b32 v255, s0, 21
	v_add3_u32 v146, 0, v48, v49
	v_or_b32_e32 v48, v58, v50
	v_writelane_b32 v255, s1, 22
	v_cmp_lt_i32_e64 s[0:1], s40, v65
	v_mul_lo_u32 v48, v48, s4
	v_add3_u32 v147, 0, v48, v49
	v_writelane_b32 v255, s0, 23
	v_or_b32_e32 v48, v59, v50
	v_mul_lo_u32 v48, v48, s4
	v_writelane_b32 v255, s1, 24
	v_cmp_lt_i32_e64 s[0:1], s93, v66
	v_add3_u32 v148, 0, v48, v49
	v_or_b32_e32 v48, v60, v50
	v_writelane_b32 v255, s0, 25
	v_mul_lo_u32 v48, v48, s4
	v_add3_u32 v149, 0, v48, v49
	v_writelane_b32 v255, s1, 26
	v_cmp_lt_i32_e64 s[0:1], s93, v67
	v_or_b32_e32 v48, v61, v50
	v_mul_lo_u32 v48, v48, s4
	v_writelane_b32 v255, s0, 27
	v_add3_u32 v150, 0, v48, v49
	v_mul_u32_u24_e32 v48, 0x88, v50
	v_writelane_b32 v255, s1, 28
	v_cmp_lt_i32_e64 s[0:1], s93, v68
	v_and_b32_e32 v49, 0xffffffc0, v136
	v_add_u32_e32 v49, 0, v49
	v_writelane_b32 v255, s0, 29
	v_lshlrev_b32_e32 v48, 2, v48
	v_add3_u32 v151, v49, v3, v48
	v_writelane_b32 v255, s1, 30
	v_cmp_lt_i32_e64 s[0:1], s40, v68
	v_cmp_lt_i32_e64 s[4:5], s44, v84
	v_cmp_lt_i32_e64 s[44:45], s44, v152
	v_writelane_b32 v255, s0, 31
	s_nop 1
	v_writelane_b32 v255, s1, 32
	v_cmp_lt_i32_e64 s[0:1], s93, v69
	s_nop 1
	v_writelane_b32 v255, s0, 33
	s_nop 1
	v_writelane_b32 v255, s1, 34
	v_cmp_lt_i32_e64 s[0:1], s93, v70
	s_nop 1
	v_writelane_b32 v255, s0, 35
	s_nop 1
	v_writelane_b32 v255, s1, 36
	v_cmp_lt_i32_e64 s[0:1], s93, v71
	s_nop 1
	v_writelane_b32 v255, s0, 37
	s_nop 1
	v_writelane_b32 v255, s1, 38
	v_cmp_lt_i32_e64 s[0:1], s40, v71
	s_nop 1
	v_writelane_b32 v255, s0, 39
	s_nop 1
	v_writelane_b32 v255, s1, 40
	v_cmp_lt_i32_e64 s[0:1], s93, v72
	s_nop 1
	v_writelane_b32 v255, s0, 41
	s_nop 1
	v_writelane_b32 v255, s1, 42
	v_cmp_lt_i32_e64 s[0:1], s93, v73
	s_nop 1
	v_writelane_b32 v255, s0, 43
	s_nop 1
	v_writelane_b32 v255, s1, 44
	v_cmp_lt_i32_e64 s[0:1], s93, v74
	s_nop 1
	v_writelane_b32 v255, s0, 45
	s_nop 1
	v_writelane_b32 v255, s1, 46
	v_cmp_lt_i32_e64 s[0:1], s40, v74
	s_nop 1
	v_writelane_b32 v255, s0, 47
	s_nop 1
	v_writelane_b32 v255, s1, 48
	v_cmp_lt_i32_e64 s[0:1], s93, v75
	s_nop 1
	v_writelane_b32 v255, s0, 49
	s_nop 1
	v_writelane_b32 v255, s1, 50
	v_cmp_lt_i32_e64 s[0:1], s93, v76
	v_cmp_lt_i32_e64 s[92:93], s40, v80
	s_nop 0
	v_writelane_b32 v255, s0, 51
	s_nop 1
	v_writelane_b32 v255, s1, 52
	v_cmp_lt_i32_e64 s[0:1], s40, v83
	v_cmp_lt_i32_e64 s[40:41], s40, v131
	v_readfirstlane_b32 s100, v202
	s_nop 3
	s_lshr_b32 s100, s100, 6
	s_cmp_ge_u32 s100, 4
	s_cbranch_scc0 .Latt_prio_done
	s_setprio 1
.Latt_prio_done:
	s_branch .LBB0_750
.LBB0_749:
	s_or_b64 exec, exec, s[64:65]
	s_waitcnt vmcnt(12)
	v_mov_b64_e32 v[114:115], v[22:23]
	v_mov_b64_e32 v[106:107], v[18:19]
	v_mov_b64_e32 v[102:103], v[14:15]
	v_mov_b64_e32 v[98:99], v[10:11]
	s_waitcnt vmcnt(10)
	v_mov_b64_e32 v[90:91], v[46:47]
	v_mov_b64_e32 v[94:95], v[42:43]
	v_mov_b64_e32 v[122:123], v[26:27]
	v_mov_b64_e32 v[118:119], v[38:39]
	v_mov_b64_e32 v[126:127], v[34:35]
	v_mov_b64_e32 v[110:111], v[30:31]
	s_add_i32 s78, s78, s28
	v_mov_b64_e32 v[112:113], v[20:21]
	v_mov_b64_e32 v[104:105], v[16:17]
	v_mov_b64_e32 v[100:101], v[12:13]
	v_mov_b64_e32 v[96:97], v[8:9]
	v_mov_b64_e32 v[88:89], v[44:45]
	v_mov_b64_e32 v[92:93], v[40:41]
	v_mov_b64_e32 v[120:121], v[24:25]
	v_mov_b64_e32 v[116:117], v[36:37]
	v_mov_b64_e32 v[124:125], v[32:33]
	v_mov_b64_e32 v[108:109], v[28:29]
	s_waitcnt vmcnt(4)
	v_mov_b64_e32 v[40:41], v[84:85]
	v_mov_b64_e32 v[44:45], v[80:81]
	v_mov_b64_e32 v[28:29], v[76:77]
	v_mov_b64_e32 v[32:33], v[72:73]
	v_mov_b64_e32 v[36:37], v[68:69]
	v_mov_b64_e32 v[20:21], v[60:61]
	v_mov_b64_e32 v[16:17], v[56:57]
	v_mov_b64_e32 v[12:13], v[52:53]
	v_mov_b64_e32 v[8:9], v[48:49]
	v_mov_b64_e32 v[24:25], v[64:65]
	s_cmpk_gt_i32 s78, 0x17ff
	v_mov_b64_e32 v[42:43], v[86:87]
	v_mov_b64_e32 v[46:47], v[82:83]
	v_mov_b64_e32 v[30:31], v[78:79]
	v_mov_b64_e32 v[34:35], v[74:75]
	v_mov_b64_e32 v[38:39], v[70:71]
	v_mov_b64_e32 v[22:23], v[62:63]
	v_mov_b64_e32 v[18:19], v[58:59]
	v_mov_b64_e32 v[14:15], v[54:55]
	v_mov_b64_e32 v[10:11], v[50:51]
	v_mov_b64_e32 v[26:27], v[66:67]
	s_cbranch_scc1 .LBB0_754

.LBB0_754:
	s_setprio 0
	s_movk_i32 s93, 0x7f
